# forget-gate cumulative sums published explicitly to the other batch classes (write-through stores + done count checked before the attention phase); closes a cross-XCD dependency the per-class barrier
# baseline (speedup 1.0000x reference)
; __device__ __forceinline__ void fcumsum(Frame& F) {
;     const int gw = F.vcu * NWAVES + F.wave;
;     if (gw >= BATCH * NH) return;
;     const int b = gw >> 3, h = gw & 7;
;     const float* src = F.logf + ((size_t)b * SEQ + 32 * F.lane) * 8 + h;
;     float v[32], tot = 0.f;
; #pragma unroll
;     for (int i = 0; i < 32; ++i) v[i] = src[i * 8];
; #pragma unroll
;     for (int i = 0; i < 32; ++i) tot += v[i];
.LBB0_155:
	s_add_u32 s0, s62, 0x2c00000
	s_addc_u32 s1, s63, 0
	s_add_u32 s47, s62, 0xc000000
	v_writelane_b32 v247, s0, 49
	s_addc_u32 s84, s63, 0
	s_nop 0
	v_writelane_b32 v247, s1, 50
	s_add_u32 s0, s62, 0x180000
	v_writelane_b32 v247, s0, 51
	s_addc_u32 s0, s63, 0
	v_writelane_b32 v247, s0, 52
	s_add_u32 s0, s62, 0xe000000
	s_addc_u32 s1, s63, 0
	v_writelane_b32 v247, s0, 53
	s_nop 1
	v_writelane_b32 v247, s1, 54
	s_add_u32 s0, s62, 0x2700000
	s_addc_u32 s1, s63, 0
	v_writelane_b32 v247, s0, 55
	s_add_u32 s82, s62, 0x5000000
	s_addc_u32 s83, s63, 0
	v_writelane_b32 v247, s1, 56
	v_writelane_b32 v247, s56, 57
	s_cmp_lt_i32 s18, 2
	s_cselect_b64 s[0:1], -1, 0
	v_writelane_b32 v247, s57, 58
	s_cmp_gt_i32 s19, 1
	v_writelane_b32 v247, s58, 59
	s_cselect_b64 s[2:3], -1, 0
	v_writelane_b32 v247, s59, 60
	s_and_b64 s[0:1], s[0:1], s[2:3]
	v_writelane_b32 v247, s60, 61
	s_andn2_b64 vcc, exec, s[0:1]
	v_writelane_b32 v247, s61, 62
	v_writelane_b32 v247, s62, 63
	v_writelane_b32 v246, s63, 0
	s_cbranch_vccnz .LBB0_375
	s_lshl_b32 s0, s89, 3
	s_add_i32 s0, s0, s81
	s_cmp_gt_i32 s0, 63
	s_cbranch_scc1 .LBB0_158
	s_ashr_i32 s2, s0, 3
	s_ashr_i32 s3, s2, 31
	s_lshl_b64 s[2:3], s[2:3], 16
	s_add_u32 s2, s62, s2
	s_addc_u32 s3, s63, s3
	v_lshlrev_b32_e32 v2, 10, v178
	v_mov_b32_e32 v3, 0
	s_lshr_b32 s1, s88, 4
	s_mov_b32 s5, 0
	v_lshl_add_u64 v[2:3], s[2:3], 0, v[2:3]
	s_and_b32 s4, s1, 28
	v_lshl_add_u64 v[2:3], v[2:3], 0, s[4:5]
	s_mov_b64 s[2:3], 0x100000
	s_mov_b32 s1, 0x100000
	v_lshl_add_u64 v[4:5], v[2:3], 0, s[2:3]
	v_add_co_u32_e32 v2, vcc, s1, v2
	s_ashr_i32 s1, s0, 31
	s_nop 0
	v_addc_co_u32_e32 v3, vcc, 0, v3, vcc
	global_load_dword v1, v[2:3], off
	s_nop 0
	global_load_dword v3, v[4:5], off offset:32
	global_load_dword v6, v[4:5], off offset:64
	global_load_dword v7, v[4:5], off offset:96
	global_load_dword v8, v[4:5], off offset:128
	global_load_dword v9, v[4:5], off offset:160
	global_load_dword v10, v[4:5], off offset:192
	global_load_dword v11, v[4:5], off offset:224
	global_load_dword v12, v[4:5], off offset:256
	global_load_dword v13, v[4:5], off offset:288
	global_load_dword v14, v[4:5], off offset:320
	global_load_dword v15, v[4:5], off offset:352
	global_load_dword v16, v[4:5], off offset:384
	global_load_dword v17, v[4:5], off offset:416
	global_load_dword v18, v[4:5], off offset:448
	global_load_dword v19, v[4:5], off offset:480
	global_load_dword v20, v[4:5], off offset:512
	global_load_dword v21, v[4:5], off offset:544
	global_load_dword v22, v[4:5], off offset:576
	global_load_dword v23, v[4:5], off offset:608
	global_load_dword v24, v[4:5], off offset:640
	global_load_dword v25, v[4:5], off offset:672
	global_load_dword v26, v[4:5], off offset:704
	global_load_dword v27, v[4:5], off offset:736
	global_load_dword v28, v[4:5], off offset:768
	global_load_dword v29, v[4:5], off offset:800
	global_load_dword v30, v[4:5], off offset:832
	global_load_dword v31, v[4:5], off offset:864
	global_load_dword v32, v[4:5], off offset:896
	global_load_dword v33, v[4:5], off offset:928
	global_load_dword v34, v[4:5], off offset:960
	global_load_dword v35, v[4:5], off offset:992
	v_mbcnt_lo_u32_b32 v2, -1, 0
	v_mbcnt_hi_u32_b32 v2, -1, v2
	v_and_b32_e32 v4, 64, v2
	v_add_u32_e32 v5, -1, v2
	v_cmp_lt_i32_e32 vcc, v5, v4
	v_add_u32_e32 v38, -2, v2
	v_add_u32_e32 v39, -4, v2
	v_cndmask_b32_e32 v5, v5, v2, vcc
	v_lshlrev_b32_e32 v5, 2, v5
	v_cmp_lt_i32_e32 vcc, v38, v4
	s_lshl_b64 s[0:1], s[0:1], 13
	v_readlane_b32 s2, v247, 51
	v_cndmask_b32_e32 v38, v38, v2, vcc
	v_cmp_eq_u32_e32 vcc, 0, v178
	v_lshlrev_b32_e32 v38, 2, v38
	s_add_u32 s0, s2, s0
	v_readlane_b32 s2, v247, 52
	v_lshlrev_b32_e32 v36, 7, v178
	s_addc_u32 s1, s2, s1
	s_waitcnt vmcnt(31)
	v_add_f32_e32 v37, 0, v1
	s_waitcnt vmcnt(30)
	v_add_f32_e32 v37, v37, v3
	s_waitcnt vmcnt(29)
	v_add_f32_e32 v37, v37, v6
	s_waitcnt vmcnt(28)
	v_add_f32_e32 v37, v37, v7
	s_waitcnt vmcnt(27)
	v_add_f32_e32 v37, v37, v8
	s_waitcnt vmcnt(26)
	v_add_f32_e32 v37, v37, v9
	s_waitcnt vmcnt(25)
	v_add_f32_e32 v37, v37, v10
	s_waitcnt vmcnt(24)
	v_add_f32_e32 v37, v37, v11
	s_waitcnt vmcnt(23)
; __device__ __forceinline__ void fcumsum(Frame& F) {
;     ...
;     float incl = tot;
; #pragma unroll
;     for (int off = 1; off < 64; off <<= 1) { const float y = __shfl_up(incl, off); if (F.lane >= off) incl += y; }
;     float run = incl - tot;
;     float* dst = F.FC + (size_t)gw * SEQ + 32 * F.lane;
; #pragma unroll
;     for (int i = 0; i < 32; i += 4) { f32x4 o; run += v[i]; o.x = run; run += v[i + 1]; o.y = run; run += v[i + 2]; o.z = run; run += v[i + 3]; o.w = run; *(f32x4*)(dst + i) = o; }
; }
	v_add_f32_e32 v37, v37, v12
	s_waitcnt vmcnt(22)
	v_add_f32_e32 v37, v37, v13
	s_waitcnt vmcnt(21)
	v_add_f32_e32 v37, v37, v14
	s_waitcnt vmcnt(20)
	v_add_f32_e32 v37, v37, v15
	s_waitcnt vmcnt(19)
	v_add_f32_e32 v37, v37, v16
	s_waitcnt vmcnt(18)
	v_add_f32_e32 v37, v37, v17
	s_waitcnt vmcnt(17)
	v_add_f32_e32 v37, v37, v18
	s_waitcnt vmcnt(16)
	v_add_f32_e32 v37, v37, v19
	s_waitcnt vmcnt(15)
	v_add_f32_e32 v37, v37, v20
	s_waitcnt vmcnt(14)
	v_add_f32_e32 v37, v37, v21
	s_waitcnt vmcnt(13)
	v_add_f32_e32 v37, v37, v22
	s_waitcnt vmcnt(12)
	v_add_f32_e32 v37, v37, v23
	s_waitcnt vmcnt(11)
	v_add_f32_e32 v37, v37, v24
	s_waitcnt vmcnt(10)
	v_add_f32_e32 v37, v37, v25
	s_waitcnt vmcnt(9)
	v_add_f32_e32 v37, v37, v26
	s_waitcnt vmcnt(8)
	v_add_f32_e32 v37, v37, v27
	s_waitcnt vmcnt(7)
	v_add_f32_e32 v37, v37, v28
	s_waitcnt vmcnt(6)
	v_add_f32_e32 v37, v37, v29
	s_waitcnt vmcnt(5)
	v_add_f32_e32 v37, v37, v30
	s_waitcnt vmcnt(4)
	v_add_f32_e32 v37, v37, v31
	s_waitcnt vmcnt(3)
	v_add_f32_e32 v37, v37, v32
	s_waitcnt vmcnt(2)
	v_add_f32_e32 v37, v37, v33
	s_waitcnt vmcnt(1)
	v_add_f32_e32 v37, v37, v34
	s_waitcnt vmcnt(0)
	v_add_f32_e32 v37, v37, v35
	ds_bpermute_b32 v5, v5, v37
	s_waitcnt lgkmcnt(0)
	v_add_f32_e32 v5, v37, v5
	v_cndmask_b32_e32 v5, v5, v37, vcc
	ds_bpermute_b32 v38, v38, v5
	v_cmp_lt_i32_e32 vcc, v39, v4
	s_waitcnt lgkmcnt(0)
	v_add_f32_e32 v38, v5, v38
	v_cndmask_b32_e32 v39, v39, v2, vcc
	v_cmp_gt_u32_e32 vcc, 2, v178
	v_lshlrev_b32_e32 v39, 2, v39
	s_nop 0
	v_cndmask_b32_e32 v5, v38, v5, vcc
	ds_bpermute_b32 v38, v39, v5
	v_add_u32_e32 v39, -8, v2
	v_cmp_lt_i32_e32 vcc, v39, v4
	s_waitcnt lgkmcnt(0)
	v_add_f32_e32 v38, v5, v38
	v_cndmask_b32_e32 v39, v39, v2, vcc
	v_cmp_gt_u32_e32 vcc, 4, v178
	v_lshlrev_b32_e32 v39, 2, v39
	s_nop 0
	v_cndmask_b32_e32 v5, v38, v5, vcc
	ds_bpermute_b32 v38, v39, v5
	v_add_u32_e32 v39, -16, v2
	v_cmp_lt_i32_e32 vcc, v39, v4
	s_waitcnt lgkmcnt(0)
	v_add_f32_e32 v38, v5, v38
	v_cndmask_b32_e32 v39, v39, v2, vcc
	v_cmp_gt_u32_e32 vcc, 8, v178
	v_lshlrev_b32_e32 v39, 2, v39
	s_nop 0
	v_cndmask_b32_e32 v5, v38, v5, vcc
	ds_bpermute_b32 v38, v39, v5
	v_subrev_u32_e32 v39, 32, v2
	v_cmp_lt_i32_e32 vcc, v39, v4
	s_waitcnt lgkmcnt(0)
	v_add_f32_e32 v4, v5, v38
	v_cndmask_b32_e32 v2, v39, v2, vcc
	v_cmp_gt_u32_e32 vcc, 16, v178
	v_lshlrev_b32_e32 v2, 2, v2
	s_nop 0
	v_cndmask_b32_e32 v4, v4, v5, vcc
	ds_bpermute_b32 v2, v2, v4
	v_cmp_gt_u32_e32 vcc, 32, v178
	s_waitcnt lgkmcnt(0)
	v_add_f32_e32 v2, v4, v2
	v_cndmask_b32_e32 v2, v2, v4, vcc
	v_sub_f32_e32 v2, v2, v37
	v_add_f32_e32 v2, v1, v2
	v_add_f32_e32 v3, v3, v2
	v_add_f32_e32 v4, v6, v3
	v_add_f32_e32 v5, v7, v4
	global_store_dwordx4 v36, v[2:5], s[0:1] sc1
	s_nop 1
	v_add_f32_e32 v2, v8, v5
	v_add_f32_e32 v3, v9, v2
	v_add_f32_e32 v4, v10, v3
	v_add_f32_e32 v5, v11, v4
	global_store_dwordx4 v36, v[2:5], s[0:1] offset:16 sc1
	s_nop 1
	v_add_f32_e32 v2, v12, v5
	v_add_f32_e32 v3, v13, v2
	v_add_f32_e32 v4, v14, v3
	v_add_f32_e32 v5, v15, v4
	global_store_dwordx4 v36, v[2:5], s[0:1] offset:32 sc1
	s_nop 1
	v_add_f32_e32 v2, v16, v5
	v_add_f32_e32 v3, v17, v2
	v_add_f32_e32 v4, v18, v3
	v_add_f32_e32 v5, v19, v4
	global_store_dwordx4 v36, v[2:5], s[0:1] offset:48 sc1
	s_nop 1
	v_add_f32_e32 v2, v20, v5
	v_add_f32_e32 v3, v21, v2
	v_add_f32_e32 v4, v22, v3
	v_add_f32_e32 v5, v23, v4
	global_store_dwordx4 v36, v[2:5], s[0:1] offset:64 sc1
	s_nop 1
	v_add_f32_e32 v2, v24, v5
	v_add_f32_e32 v3, v25, v2
	v_add_f32_e32 v4, v26, v3
	v_add_f32_e32 v5, v27, v4
	global_store_dwordx4 v36, v[2:5], s[0:1] offset:80 sc1
	s_nop 1
	v_add_f32_e32 v2, v28, v5
	v_add_f32_e32 v3, v29, v2
	v_add_f32_e32 v4, v30, v3
	v_add_f32_e32 v5, v31, v4
	global_store_dwordx4 v36, v[2:5], s[0:1] offset:96 sc1
	s_nop 1
	v_add_f32_e32 v2, v32, v5
	v_add_f32_e32 v3, v33, v2
	v_add_f32_e32 v4, v34, v3
	v_add_f32_e32 v5, v35, v4
	global_store_dwordx4 v36, v[2:5], s[0:1] offset:112 sc1
	s_waitcnt vmcnt(0)
	s_mov_b64 s[2:3], exec
	s_mov_b64 exec, 1
	s_add_u32 s0, s62, 0xd100
	s_addc_u32 s1, s63, 0
	v_mov_b32_e32 v240, 0
	v_mov_b32_e32 v241, 1
	global_atomic_add v240, v241, s[0:1]
	s_mov_b64 exec, s[2:3]

; __device__ __forceinline__ unsigned xb_ld(unsigned* p)              { return __hip_atomic_load(p, __ATOMIC_RELAXED, __HIP_MEMORY_SCOPE_AGENT); }
; __device__ __forceinline__ unsigned xb_add(unsigned* p, unsigned v) { return __hip_atomic_fetch_add(p, v, __ATOMIC_RELAXED, __HIP_MEMORY_SCOPE_AGENT); }
; #define XB_SPIN(cond, bar) do { unsigned _sp = 0; while (cond) { __builtin_amdgcn_s_sleep(1); \
;     if ((++_sp & 255u) == 0u) { if (xb_ld(&(bar)[XB_TMO])) break; if (_sp > XB_SPIN_CAP) { atomicAdd(&(bar)[XB_TMO], 1u); break; } } } } while (0)
; __device__ __forceinline__ void xcd_barrier(const XcdBarrier& b) {
;     ...
;         const unsigned old = xb_add(&bar[XB_XSUB(b.x)], 1u);
;         const unsigned gen = old / nloc;
;         if (old + 1u == (gen + 1u) * nloc) {
;             __builtin_amdgcn_fence(__ATOMIC_RELEASE, "agent");
;             asm volatile("s_waitcnt vmcnt(0)" ::: "memory");
;             const unsigned og = xb_add(&bar[XB_TOP], 1u);
;             const unsigned tg = og / nx;
;             if (og + 1u == (tg + 1u) * nx) xb_add(&bar[XB_TOPGEN], 1u);
;             else XB_SPIN(xb_ld(&bar[XB_TOPGEN]) == tg, bar);
;             __builtin_amdgcn_fence(__ATOMIC_ACQUIRE, "agent");
;             xb_add(&bar[XB_XGEN(b.x)], 1u);
;             asm volatile("s_waitcnt vmcnt(0)" ::: "memory");
;         } else {
;             XB_SPIN(xb_ld(&bar[XB_XGEN(b.x)]) == gen, bar);
;             __builtin_amdgcn_fence(__ATOMIC_ACQUIRE, "agent");
;             asm volatile("s_waitcnt vmcnt(0)" ::: "memory");
;         }
.Lgrpbar3_same:
	buffer_inv sc1
	global_atomic_add v1, v2, s[2:3]
	global_atomic_add v1, v2, s[6:7]
	s_add_u32 s8, s62, 0xd100
	s_addc_u32 s9, s63, 0
.Lgrpbar3_spin:
	global_load_dword v3, v1, s[2:3] sc1
	global_load_dword v4, v1, s[8:9] sc1
	s_waitcnt vmcnt(0)
	v_cmp_lt_u32_e32 vcc, 31, v3
	s_cbranch_vccz .Lgrpbar3_retry
	v_cmp_lt_u32_e32 vcc, 63, v4
	s_cbranch_vccnz .Lgrpbar3_done
